# conv walker: the 4 row loads and the dt operand loads of an iteration issued together at its top (one wait), instead of load-wait per row
# speedup vs baseline: 1.0208x; 1.0203x over previous
; __device__ __forceinline__ uint4 pack8(const float* f) { uint4 o; o.x = pk2(f[0], f[1]); o.y = pk2(f[2], f[3]); o.z = pk2(f[4], f[5]); o.w = pk2(f[6], f[7]); return o; }
; __device__ __forceinline__ float silu_f(float x) { return x * __builtin_amdgcn_rcpf(1.0f + __expf(-x)); }
; __device__ __forceinline__ void phase_ssd_conv_dt(const Args& a, int j) {
;     ...
;     for (int t = 0; t < 64; ++t) {
;         float cur[8], o[8];
;         unpack8(*(const uint4*)(p + (size_t)t * BIGW), cur);
;         if (has_dt && !(t & 1)) {
;             const int k0 = (t >> 1) * 32;
;             const bf16x8 xf = *(const bf16x8*)(xp + k0), wf0 = *(const bf16x8*)(w0p + k0), wf1 = *(const bf16x8*)(w1p + k0);
;             d0 = __builtin_amdgcn_mfma_f32_16x16x32_bf16(wf0, xf, d0, 0, 0, 0);
;             d1 = __builtin_amdgcn_mfma_f32_16x16x32_bf16(wf1, xf, d1, 0, 0, 0);
;         }
; #pragma unroll
;         for (int e = 0; e < 8; ++e) { const float v = bb[e] + wt[0][e] * h0[e] + wt[1][e] * h1[e] + wt[2][e] * h2[e] + wt[3][e] * cur[e]; o[e] = silu_f(v); h0[e] = h1[e]; h1[e] = h2[e]; h2[e] = cur[e]; }
;         *(uint4*)(p + (size_t)t * BIGW) = pack8(o);
;     }
.LBB0_798:
	s_nop 0
	v_lshlrev_b32_e32 v85, 16, v120
	v_and_b32_e32 v84, 0xffff0000, v120
	v_lshlrev_b32_e32 v73, 16, v122
	v_fma_f32 v58, v22, v89, v54
	v_and_b32_e32 v72, 0xffff0000, v122
	v_fma_f32 v60, v23, v88, v55
	v_fma_f32 v83, v24, v83, v56
	v_fmac_f32_e32 v58, v26, v106
	v_fmac_f32_e32 v60, v27, v105
	v_fmac_f32_e32 v83, v28, v104
	v_lshlrev_b32_e32 v77, 16, v121
	v_fmac_f32_e32 v58, v34, v75
	v_fmac_f32_e32 v60, v35, v74
	v_fmac_f32_e32 v83, v36, v71
	v_fmac_f32_e32 v58, v42, v85
	v_fmac_f32_e32 v60, v43, v84
	v_fmac_f32_e32 v83, v44, v77
	v_and_b32_e32 v76, 0xffff0000, v121
	v_mul_f32_e32 v59, 0xbfb8aa3b, v58
	v_lshlrev_b32_e32 v69, 16, v123
	v_and_b32_e32 v68, 0xffff0000, v123
	v_mul_f32_e32 v61, 0xbfb8aa3b, v60
	v_mul_f32_e32 v88, 0xbfb8aa3b, v83
	v_exp_f32_e32 v59, v59
	v_exp_f32_e32 v61, v61
	v_exp_f32_e32 v88, v88
	v_fma_f32 v82, v25, v82, v57
	v_fmac_f32_e32 v82, v29, v103
	v_fmac_f32_e32 v82, v37, v70
	v_fmac_f32_e32 v82, v45, v76
	v_add_f32_e32 v59, 1.0, v59
	v_add_f32_e32 v61, 1.0, v61
	v_add_f32_e32 v88, 1.0, v88
	v_mul_f32_e32 v89, 0xbfb8aa3b, v82
	v_rcp_f32_e32 v59, v59
	v_rcp_f32_e32 v61, v61
	v_rcp_f32_e32 v88, v88
	v_exp_f32_e32 v89, v89
	v_fma_f32 v81, v18, v81, v50
	v_fma_f32 v80, v19, v80, v51
	v_fmac_f32_e32 v81, v30, v102
	v_fmac_f32_e32 v80, v31, v101
	v_fmac_f32_e32 v81, v38, v67
	v_fmac_f32_e32 v80, v39, v66
	v_fmac_f32_e32 v81, v46, v73
	v_fmac_f32_e32 v80, v47, v72
	v_mul_f32_e32 v58, v58, v59
	v_mul_f32_e32 v59, v60, v61
	v_mul_f32_e32 v60, v83, v88
	v_add_f32_e32 v61, 1.0, v89
	v_mul_f32_e32 v83, 0xbfb8aa3b, v81
	v_mul_f32_e32 v88, 0xbfb8aa3b, v80
	v_rcp_f32_e32 v61, v61
	v_exp_f32_e32 v83, v83
	v_exp_f32_e32 v88, v88
	v_fma_f32 v79, v20, v79, v52
	v_fma_f32 v78, v21, v78, v53
	v_fmac_f32_e32 v79, v32, v2
	v_fmac_f32_e32 v78, v33, v1
	v_fmac_f32_e32 v79, v40, v65
	v_fmac_f32_e32 v78, v41, v64
	v_fmac_f32_e32 v79, v48, v69
	v_fmac_f32_e32 v78, v49, v68
	v_mul_f32_e32 v61, v82, v61
	v_add_f32_e32 v82, 1.0, v83
	v_add_f32_e32 v83, 1.0, v88
	v_mul_f32_e32 v88, 0xbfb8aa3b, v79
	v_mul_f32_e32 v89, 0xbfb8aa3b, v78
	v_exp_f32_e32 v88, v88
	v_exp_f32_e32 v89, v89
	v_rcp_f32_e32 v82, v82
	v_rcp_f32_e32 v83, v83
	v_add_f32_e32 v88, 1.0, v88
	v_add_f32_e32 v89, 1.0, v89
	v_rcp_f32_e32 v88, v88
	v_rcp_f32_e32 v89, v89
	v_add_co_u32_e32 v98, vcc, s8, v4
	v_mul_f32_e32 v81, v81, v82
	s_nop 0
	v_addc_co_u32_e32 v99, vcc, 0, v5, vcc
	v_mul_f32_e32 v80, v80, v83
	v_mul_f32_e32 v79, v79, v88
	v_mul_f32_e32 v78, v78, v89
	v_cvt_pk_bf16_f32 v58, v58, v59
	v_cvt_pk_bf16_f32 v59, v60, v61
	v_cvt_pk_bf16_f32 v60, v81, v80
	v_cvt_pk_bf16_f32 v61, v79, v78
	s_nop 0
	s_mov_b64 s[2:3], 0x9307000
	v_lshl_add_u64 v[4:5], v[4:5], 0, s[2:3]
	global_store_dwordx4 v[4:5], v[58:61], off
	v_fma_f32 v4, v22, v106, v54
	v_fmac_f32_e32 v4, v26, v75
	v_fma_f32 v58, v23, v105, v55
	v_fma_f32 v60, v24, v104, v56
	v_fmac_f32_e32 v58, v27, v74
	v_fmac_f32_e32 v60, v28, v71
	v_fmac_f32_e32 v4, v34, v85
	v_fmac_f32_e32 v58, v35, v84
	v_fmac_f32_e32 v60, v36, v77
	v_fma_f32 v2, v20, v2, v52
	v_fma_f32 v1, v21, v1, v53
	v_fmac_f32_e32 v2, v32, v65
	v_fmac_f32_e32 v1, v33, v64
	v_fmac_f32_e32 v2, v40, v69
	v_fmac_f32_e32 v1, v41, v68
	s_add_i32 s0, s0, -4
	v_lshl_add_u64 v[86:87], v[86:87], 0, s[10:11]
	v_lshl_add_u64 v[90:91], v[90:91], 0, s[70:71]
	s_cmp_eq_u32 s0, 0
	v_lshl_add_u64 v[92:93], v[92:93], 0, s[70:71]
	s_nop 0
	v_lshlrev_b32_e32 v89, 16, v124
	v_and_b32_e32 v88, 0xffff0000, v124
	v_lshlrev_b32_e32 v83, 16, v125
	v_fmac_f32_e32 v4, v42, v89
	v_fmac_f32_e32 v58, v43, v88
	v_fmac_f32_e32 v60, v44, v83
	v_mul_f32_e32 v5, 0xbfb8aa3b, v4
	v_mul_f32_e32 v59, 0xbfb8aa3b, v58
	v_mul_f32_e32 v61, 0xbfb8aa3b, v60
	v_exp_f32_e32 v5, v5
	v_exp_f32_e32 v59, v59
	v_exp_f32_e32 v61, v61
	v_fma_f32 v94, v25, v103, v57
	v_fmac_f32_e32 v94, v29, v70
	v_and_b32_e32 v82, 0xffff0000, v125
	v_fmac_f32_e32 v94, v37, v76
	v_fmac_f32_e32 v94, v45, v82
	v_add_f32_e32 v5, 1.0, v5
	v_add_f32_e32 v59, 1.0, v59
	v_add_f32_e32 v61, 1.0, v61
	v_mul_f32_e32 v95, 0xbfb8aa3b, v94
	v_rcp_f32_e32 v5, v5
	v_rcp_f32_e32 v59, v59
	v_rcp_f32_e32 v61, v61
	v_exp_f32_e32 v95, v95
	v_mul_f32_e32 v4, v4, v5
	v_mul_f32_e32 v5, v58, v59
	v_mul_f32_e32 v59, v60, v61
	v_add_f32_e32 v58, 1.0, v95
	v_fma_f32 v60, v18, v102, v50
	v_fma_f32 v95, v19, v101, v51
	v_fmac_f32_e32 v60, v30, v67
	v_fmac_f32_e32 v95, v31, v66
	v_lshlrev_b32_e32 v81, 16, v126
	v_and_b32_e32 v80, 0xffff0000, v126
	v_fmac_f32_e32 v60, v38, v73
	v_fmac_f32_e32 v95, v39, v72
	v_fmac_f32_e32 v60, v46, v81
	v_fmac_f32_e32 v95, v47, v80
	v_mul_f32_e32 v61, 0xbfb8aa3b, v60
	v_mul_f32_e32 v96, 0xbfb8aa3b, v95
	v_rcp_f32_e32 v58, v58
	v_exp_f32_e32 v61, v61
	v_exp_f32_e32 v96, v96
	v_lshlrev_b32_e32 v79, 16, v127
	v_and_b32_e32 v78, 0xffff0000, v127
	v_fmac_f32_e32 v2, v48, v79
	v_fmac_f32_e32 v1, v49, v78
	v_mul_f32_e32 v94, v94, v58
	v_add_f32_e32 v58, 1.0, v61
	v_add_f32_e32 v61, 1.0, v96
	v_mul_f32_e32 v96, 0xbfb8aa3b, v2
	v_mul_f32_e32 v97, 0xbfb8aa3b, v1
	v_exp_f32_e32 v96, v96
	v_exp_f32_e32 v97, v97
	v_rcp_f32_e32 v58, v58
	v_rcp_f32_e32 v61, v61
	v_add_f32_e32 v96, 1.0, v96
	v_add_f32_e32 v97, 1.0, v97
	v_rcp_f32_e32 v96, v96
	v_rcp_f32_e32 v97, v97
	v_mul_f32_e32 v60, v60, v58
	v_mul_f32_e32 v61, v95, v61
	v_mul_f32_e32 v2, v2, v96
	v_mul_f32_e32 v1, v1, v97
	v_cvt_pk_bf16_f32 v58, v4, v5
	v_cvt_pk_bf16_f32 v59, v59, v94
	v_cvt_pk_bf16_f32 v60, v60, v61
	v_cvt_pk_bf16_f32 v61, v2, v1
	global_store_dwordx4 v[98:99], v[58:61], off
	s_cbranch_scc1 .LBB0_803
; __device__ __forceinline__ void phase_ssd_conv_dt(const Args& a, int j) {
;     ...
;     for (int t = 0; t < 64; ++t) {
;         float cur[8], o[8];
;         unpack8(*(const uint4*)(p + (size_t)t * BIGW), cur);
;         if (has_dt && !(t & 1)) {
;             const int k0 = (t >> 1) * 32;
;             const bf16x8 xf = *(const bf16x8*)(xp + k0), wf0 = *(const bf16x8*)(w0p + k0), wf1 = *(const bf16x8*)(w1p + k0);
;             d0 = __builtin_amdgcn_mfma_f32_16x16x32_bf16(wf0, xf, d0, 0, 0, 0);
;             d1 = __builtin_amdgcn_mfma_f32_16x16x32_bf16(wf1, xf, d1, 0, 0, 0);
;         }
.LBB0_799:
	v_lshl_add_u64 v[4:5], s[30:31], 0, v[86:87]
	v_add_co_u32_e32 v58, vcc, 0x9301000, v4
	v_cndmask_b32_e64 v1, 0, 1, s[4:5]
	s_nop 0
	v_addc_co_u32_e32 v59, vcc, 0, v5, vcc
	global_load_dwordx4 v[112:115], v[58:59], off
	v_add_co_u32_e32 v58, vcc, s1, v4
	s_nop 1
	v_addc_co_u32_e32 v59, vcc, 0, v5, vcc
	global_load_dwordx4 v[116:119], v[58:59], off
	v_add_co_u32_e32 v58, vcc, 0x9307000, v4
	s_nop 1
	v_addc_co_u32_e32 v59, vcc, 0, v5, vcc
	global_load_dwordx4 v[120:123], v[58:59], off
	v_add_co_u32_e32 v58, vcc, s8, v4
	s_nop 1
	v_addc_co_u32_e32 v59, vcc, 0, v5, vcc
	global_load_dwordx4 v[124:127], v[58:59], off
	v_cmp_ne_u32_e64 s[6:7], 1, v1
	s_andn2_b64 vcc, exec, s[4:5]
	v_lshl_add_u64 v[96:97], s[30:31], 0, v[92:93]
	v_lshl_add_u64 v[94:95], s[30:31], 0, v[90:91]
	s_cbranch_vccnz .LBB0_801
	v_add_co_u32_e32 v98, vcc, 0x7300000, v96
	s_nop 1
	v_addc_co_u32_e32 v99, vcc, 0, v97, vcc
	v_add_co_u32_e32 v102, vcc, 0xc00000, v94
	s_nop 1
	v_addc_co_u32_e32 v103, vcc, 0, v95, vcc
	global_load_dwordx4 v[128:131], v[102:103], off
	global_load_dwordx4 v[132:135], v[98:99], off
	global_load_dwordx4 v[140:143], v[102:103], off offset:64
	global_load_dwordx4 v[144:147], v[98:99], off offset:64
	v_add_co_u32_e32 v98, vcc, 0xc08000, v94
	s_nop 1
	v_addc_co_u32_e32 v99, vcc, 0, v95, vcc
	global_load_dwordx4 v[136:139], v[98:99], off
	global_load_dwordx4 v[148:151], v[98:99], off offset:64
	s_waitcnt vmcnt(0)
	v_mfma_f32_16x16x32_bf16 v[14:17], v[128:131], v[132:135], v[14:17]
	v_mfma_f32_16x16x32_bf16 v[10:13], v[136:139], v[132:135], v[10:13]
	v_mfma_f32_16x16x32_bf16 v[14:17], v[140:143], v[144:147], v[14:17]
	v_mfma_f32_16x16x32_bf16 v[10:13], v[148:151], v[144:147], v[10:13]
; __device__ __forceinline__ uint4 pack8(const float* f) { uint4 o; o.x = pk2(f[0], f[1]); o.y = pk2(f[2], f[3]); o.z = pk2(f[4], f[5]); o.w = pk2(f[6], f[7]); return o; }
; __device__ __forceinline__ float silu_f(float x) { return x * __builtin_amdgcn_rcpf(1.0f + __expf(-x)); }
; __device__ __forceinline__ void phase_ssd_conv_dt(const Args& a, int j) {
;     ...
;     for (int t = 0; t < 64; ++t) {
;         float cur[8], o[8];
;         unpack8(*(const uint4*)(p + (size_t)t * BIGW), cur);
;         if (has_dt && !(t & 1)) {
;             const int k0 = (t >> 1) * 32;
;             const bf16x8 xf = *(const bf16x8*)(xp + k0), wf0 = *(const bf16x8*)(w0p + k0), wf1 = *(const bf16x8*)(w1p + k0);
;             d0 = __builtin_amdgcn_mfma_f32_16x16x32_bf16(wf0, xf, d0, 0, 0, 0);
;             d1 = __builtin_amdgcn_mfma_f32_16x16x32_bf16(wf1, xf, d1, 0, 0, 0);
;         }
; #pragma unroll
;         for (int e = 0; e < 8; ++e) { const float v = bb[e] + wt[0][e] * h0[e] + wt[1][e] * h1[e] + wt[2][e] * h2[e] + wt[3][e] * cur[e]; o[e] = silu_f(v); h0[e] = h1[e]; h1[e] = h2[e]; h2[e] = cur[e]; }
;         *(uint4*)(p + (size_t)t * BIGW) = pack8(o);
;     }
.LBB0_801:
	s_waitcnt vmcnt(0)
	v_lshlrev_b32_e32 v106, 16, v112
	v_and_b32_e32 v105, 0xffff0000, v112
	v_fma_f32 v58, v22, v75, v54
	v_fmac_f32_e32 v58, v26, v85
	v_fmac_f32_e32 v58, v34, v89
	v_fmac_f32_e32 v58, v42, v106
	v_lshlrev_b32_e32 v104, 16, v113
	v_and_b32_e32 v103, 0xffff0000, v113
	v_mul_f32_e32 v59, 0xbfb8aa3b, v58
	v_exp_f32_e32 v59, v59
	v_lshlrev_b32_e32 v102, 16, v114
	v_and_b32_e32 v101, 0xffff0000, v114
	v_lshlrev_b32_e32 v2, 16, v115
	v_add_f32_e32 v59, 1.0, v59
	v_rcp_f32_e32 v59, v59
	v_and_b32_e32 v1, 0xffff0000, v115
	v_fma_f32 v67, v18, v67, v50
	v_fmac_f32_e32 v67, v30, v73
	v_mul_f32_e32 v58, v58, v59
	v_fma_f32 v59, v23, v74, v55
	v_fmac_f32_e32 v59, v27, v84
	v_fmac_f32_e32 v59, v35, v88
	v_fmac_f32_e32 v59, v43, v105
	v_mul_f32_e32 v60, 0xbfb8aa3b, v59
	v_exp_f32_e32 v60, v60
	v_fmac_f32_e32 v67, v38, v81
	v_fmac_f32_e32 v67, v46, v102
	v_fma_f32 v66, v19, v66, v51
	v_add_f32_e32 v60, 1.0, v60
	v_rcp_f32_e32 v60, v60
	v_fmac_f32_e32 v66, v31, v72
	v_fmac_f32_e32 v66, v39, v80
	v_fmac_f32_e32 v66, v47, v101
	v_mul_f32_e32 v59, v59, v60
	v_fma_f32 v60, v24, v71, v56
	v_fmac_f32_e32 v60, v28, v77
	v_fmac_f32_e32 v60, v36, v83
	v_fmac_f32_e32 v60, v44, v104
	v_mul_f32_e32 v61, 0xbfb8aa3b, v60
	v_exp_f32_e32 v61, v61
	v_fma_f32 v65, v20, v65, v52
	v_fmac_f32_e32 v65, v32, v69
	v_fmac_f32_e32 v65, v40, v79
	v_add_f32_e32 v61, 1.0, v61
	v_rcp_f32_e32 v61, v61
	v_fmac_f32_e32 v65, v48, v2
	v_fma_f32 v64, v21, v64, v53
	v_fmac_f32_e32 v64, v33, v68
	v_mul_f32_e32 v60, v60, v61
	v_fma_f32 v61, v25, v70, v57
	v_fmac_f32_e32 v61, v29, v76
	v_fmac_f32_e32 v61, v37, v82
	v_fmac_f32_e32 v61, v45, v103
	v_mul_f32_e32 v70, 0xbfb8aa3b, v61
	v_exp_f32_e32 v70, v70
	v_fmac_f32_e32 v64, v41, v78
	v_fmac_f32_e32 v64, v49, v1
	s_mov_b64 s[2:3], 0x9301000
	v_add_f32_e32 v70, 1.0, v70
	v_rcp_f32_e32 v70, v70
	v_lshl_add_u64 v[98:99], v[4:5], 0, s[2:3]
	v_cvt_pk_bf16_f32 v58, v58, v59
	v_fma_f32 v77, v24, v77, v56
	v_mul_f32_e32 v61, v61, v70
	v_mul_f32_e32 v70, 0xbfb8aa3b, v67
	v_exp_f32_e32 v70, v70
	v_cvt_pk_bf16_f32 v59, v60, v61
	v_fmac_f32_e32 v77, v28, v83
	v_fmac_f32_e32 v77, v36, v104
	v_add_f32_e32 v70, 1.0, v70
	v_rcp_f32_e32 v70, v70
	v_fma_f32 v76, v25, v76, v57
	v_fmac_f32_e32 v76, v29, v82
	v_fmac_f32_e32 v76, v37, v103
	v_mul_f32_e32 v67, v67, v70
	v_mul_f32_e32 v70, 0xbfb8aa3b, v66
	v_exp_f32_e32 v70, v70
	v_fma_f32 v73, v18, v73, v50
	v_fmac_f32_e32 v73, v30, v81
	v_fmac_f32_e32 v73, v38, v102
	v_add_f32_e32 v70, 1.0, v70
	v_rcp_f32_e32 v70, v70
	v_fma_f32 v72, v19, v72, v51
	v_fmac_f32_e32 v72, v31, v80
	v_fmac_f32_e32 v72, v39, v101
	v_mul_f32_e32 v66, v66, v70
	v_mul_f32_e32 v70, 0xbfb8aa3b, v65
	v_exp_f32_e32 v70, v70
	v_cvt_pk_bf16_f32 v60, v67, v66
	v_fma_f32 v69, v20, v69, v52
	v_fmac_f32_e32 v69, v32, v79
	v_add_f32_e32 v70, 1.0, v70
	v_rcp_f32_e32 v70, v70
	v_fmac_f32_e32 v69, v40, v2
	v_fma_f32 v68, v21, v68, v53
	v_fmac_f32_e32 v68, v33, v78
	v_mul_f32_e32 v65, v65, v70
	v_mul_f32_e32 v70, 0xbfb8aa3b, v64
	v_exp_f32_e32 v70, v70
	v_fmac_f32_e32 v68, v41, v1
	v_add_f32_e32 v70, 1.0, v70
	v_rcp_f32_e32 v70, v70
	s_nop 0
	v_mul_f32_e32 v64, v64, v70
	v_cvt_pk_bf16_f32 v61, v65, v64
	global_store_dwordx4 v[98:99], v[58:61], off
	s_nop 1
	v_add_co_u32_e32 v58, vcc, s1, v4
	v_fma_f32 v60, v22, v85, v54
	s_nop 0
	v_addc_co_u32_e32 v59, vcc, 0, v5, vcc
	s_nop 0
	v_fmac_f32_e32 v60, v26, v89
	v_fmac_f32_e32 v60, v34, v106
	s_nop 0
	v_lshlrev_b32_e32 v75, 16, v116
	v_fmac_f32_e32 v60, v42, v75
	v_mul_f32_e32 v61, 0xbfb8aa3b, v60
	v_exp_f32_e32 v61, v61
	v_and_b32_e32 v74, 0xffff0000, v116
	v_lshlrev_b32_e32 v71, 16, v117
	v_fmac_f32_e32 v77, v44, v71
	v_add_f32_e32 v61, 1.0, v61
	v_rcp_f32_e32 v61, v61
	v_and_b32_e32 v70, 0xffff0000, v117
	v_fmac_f32_e32 v76, v45, v70
	v_lshlrev_b32_e32 v67, 16, v118
	v_mul_f32_e32 v60, v60, v61
	v_fma_f32 v61, v23, v84, v55
	v_fmac_f32_e32 v61, v27, v88
	v_fmac_f32_e32 v61, v35, v105
	v_fmac_f32_e32 v61, v43, v74
	v_mul_f32_e32 v84, 0xbfb8aa3b, v61
	v_exp_f32_e32 v84, v84
	v_fmac_f32_e32 v73, v46, v67
	v_and_b32_e32 v66, 0xffff0000, v118
	v_fmac_f32_e32 v72, v47, v66
	v_add_f32_e32 v84, 1.0, v84
	v_rcp_f32_e32 v84, v84
	v_lshlrev_b32_e32 v65, 16, v119
	v_fmac_f32_e32 v69, v48, v65
	v_and_b32_e32 v64, 0xffff0000, v119
	v_mul_f32_e32 v61, v61, v84
	v_mul_f32_e32 v84, 0xbfb8aa3b, v77
	v_exp_f32_e32 v84, v84
	v_fmac_f32_e32 v68, v49, v64
	v_cvt_pk_bf16_f32 v108, v60, v61
	v_add_f32_e32 v84, 1.0, v84
	v_rcp_f32_e32 v84, v84
	s_nop 0
	v_mul_f32_e32 v77, v77, v84
	v_mul_f32_e32 v84, 0xbfb8aa3b, v76
	v_exp_f32_e32 v84, v84
	s_nop 0
	v_add_f32_e32 v84, 1.0, v84
	v_rcp_f32_e32 v84, v84
	s_nop 0
	v_mul_f32_e32 v76, v76, v84
	v_mul_f32_e32 v84, 0xbfb8aa3b, v73
	v_exp_f32_e32 v84, v84
	v_cvt_pk_bf16_f32 v109, v77, v76
	s_nop 0
	v_add_f32_e32 v84, 1.0, v84
	v_rcp_f32_e32 v84, v84
	s_nop 0
	v_mul_f32_e32 v73, v73, v84
	v_mul_f32_e32 v84, 0xbfb8aa3b, v72
	v_exp_f32_e32 v84, v84
	s_nop 0
	v_add_f32_e32 v84, 1.0, v84
	v_rcp_f32_e32 v84, v84
	s_nop 0
	v_mul_f32_e32 v72, v72, v84
	v_mul_f32_e32 v84, 0xbfb8aa3b, v69
	v_exp_f32_e32 v84, v84
	v_cvt_pk_bf16_f32 v110, v73, v72
	s_nop 0
	v_add_f32_e32 v84, 1.0, v84
	v_rcp_f32_e32 v84, v84
	s_nop 0
	v_mul_f32_e32 v69, v69, v84
	v_mul_f32_e32 v84, 0xbfb8aa3b, v68
	v_exp_f32_e32 v84, v84
	s_nop 0
	v_add_f32_e32 v84, 1.0, v84
	v_rcp_f32_e32 v84, v84
	s_nop 0
	v_mul_f32_e32 v68, v68, v84
	v_cvt_pk_bf16_f32 v111, v69, v68
	global_store_dwordx4 v[58:59], v[108:111], off
	s_branch .LBB0_798
